# token seed read with a system-scope vector load instead of a scalar load (robustness); otherwise as the previous best
# baseline (speedup 1.0000x reference)
.LBB0_13:
	v_lshrrev_b32_e32 v1, 20, v0
	v_lshrrev_b32_e32 v0, 10, v0
	v_or_b32_e32 v0, v0, v1
	s_movk_i32 s4, 0x3ff
	v_and_or_b32 v0, v0, s4, v196
	v_cmp_eq_u32_e32 vcc, 0, v0
	s_waitcnt vmcnt(0)
	s_barrier
	s_and_saveexec_b64 s[4:5], vcc
	s_cbranch_execz .LBB0_23
	s_load_dwordx2 s[98:99], s[6:7], 0x58
	s_cmp_lg_u32 s2, 0
	s_cbranch_scc1 .LBB0_23
	buffer_wbl2 sc1
	s_waitcnt lgkmcnt(0)
	v_mov_b32_e32 v0, 0
	global_load_dword v1, v0, s[98:99] offset:32 sc0 sc1
	s_waitcnt vmcnt(0)
	v_readfirstlane_b32 s100, v1
	s_mul_i32 s8, s100, 0x9e3779b1
	s_add_i32 s8, s8, 0x7f4a7c15
	v_mov_b32_e32 v0, 0x7800
	v_mov_b32_e32 v1, s8
	global_store_dword v0, v1, s[70:71] sc0 sc1

.LBB0_106:
	s_cmp_gt_i32 s29, 1
	s_cselect_b64 s[4:5], -1, 0
	s_and_b64 s[0:1], s[72:73], s[4:5]
	s_andn2_b64 vcc, exec, s[0:1]
	v_cmp_eq_u32_e64 s[0:1], 0, v196
	s_cbranch_vccnz .LBB0_156
	s_waitcnt vmcnt(0)
	s_waitcnt lgkmcnt(0)
	s_barrier
	s_and_saveexec_b64 s[6:7], s[0:1]
	s_cbranch_execz .LBB0_155
	s_waitcnt lgkmcnt(0)
	v_mov_b32_e32 v0, 0
	global_load_dword v1, v0, s[98:99] offset:32 sc0 sc1
	s_waitcnt vmcnt(0)
	v_readfirstlane_b32 s100, v1
	s_mul_i32 s101, s100, 0x9e3779b1
	s_add_i32 s101, s101, 0x7f4a7c15
	v_mov_b32_e32 v0, 0x7800
	s_mov_b32 s8, 0
